# fast path v12: steady-state barrier moved before the last four tile-B PV MFMAs, which then cover barrier skew and the next iteration's tile-A K reads; prefetch loads post-barrier
# baseline (speedup 1.0000x reference)
; #define MFMA32(a, b, c) __builtin_amdgcn_mfma_f32_32x32x16_bf16((a), (b), (c), 0, 0, 0)
; DI unsigned pk_bf16(float lo, float hi) { f32x2 v = {lo, hi}; bf16v2 b = __builtin_convertvector(v, bf16v2); return __builtin_bit_cast(unsigned, b); }
; DI int crow(int r, int h) { return (r & 3) + 8 * (r >> 2) + 4 * h; }
; DI void attn_item(const Params& p, int g, int seq, int hd, int qt, int m, char* smem, int split_j, int sub) {
;     ...
;     bf16x8 kf[4], vf[2][4];
; #pragma unroll
;     for (int s = 0; s < 4; ++s) kf[s] = *(const bf16x8*)(Kb + l31 * 72 + s * 16 + h * 8);
; #pragma unroll
;     for (int s2 = 0; s2 < 2; ++s2)
; #pragma unroll
;       for (int dt = 0; dt < 4; ++dt) vf[s2][dt] = *(const bf16x8*)(Vb + (dt * 32 + l31) * 40 + s2 * 16 + h * 8);
;     __builtin_amdgcn_sched_barrier(0);
;     f32x16 X;
; #pragma unroll
;     for (int r = 0; r < 16; ++r) X[r] = 0.f;
; #pragma unroll
;     for (int s = 0; s < 4; ++s) X = MFMA32(kf[s], qf[s], X);
;     if (farL || farR) {
; #pragma unroll
;       for (int r = 0; r < 16; ++r) X[r] = __builtin_amdgcn_exp2f(X[r]);
;     } else {
;       const int rel0 = k0 - (qw0 + l31) + 128;
; #pragma unroll
;       for (int r = 0; r < 16; ++r) { int idx = rel0 + crow(r, h); idx = idx < 0 ? 0 : (idx > 256 ? 256 : idx); X[r] = __builtin_amdgcn_exp2f(X[r] + tab[idx]); }
;     }
;     bf16x8 pf[2];
; #pragma unroll
;     for (int s2 = 0; s2 < 2; ++s2) {
;       u32x4 w; w.x = pk_bf16(X[8 * s2], X[8 * s2 + 1]); w.y = pk_bf16(X[8 * s2 + 2], X[8 * s2 + 3]); w.z = pk_bf16(X[8 * s2 + 4], X[8 * s2 + 5]); w.w = pk_bf16(X[8 * s2 + 6], X[8 * s2 + 7]);
;       ls2 += (f32x2){X[8 * s2], X[8 * s2 + 1]}; ls2 += (f32x2){X[8 * s2 + 2], X[8 * s2 + 3]};
;       ls2 += (f32x2){X[8 * s2 + 4], X[8 * s2 + 5]}; ls2 += (f32x2){X[8 * s2 + 6], X[8 * s2 + 7]};
;       pf[s2] = __builtin_bit_cast(bf16x8, w);
;     }
; #pragma unroll
;     for (int s2 = 0; s2 < 2; ++s2)
; #pragma unroll
;       for (int dt = 0; dt < 4; ++dt) O[dt] = MFMA32(pf[s2], vf[s2][dt], O[dt]);
.Lat2_qka:
	s_waitcnt lgkmcnt(3)
	v_mfma_f32_32x32x16_bf16 v[64:79], v[64:67], v[104:107], 0
	ds_read_b128 v[220:223], v192 offset:4608
	ds_read_b128 v[224:227], v192 offset:4640
	ds_read_b128 v[236:239], v192 offset:4672
	ds_read_b128 v[240:243], v192 offset:4704
	s_waitcnt lgkmcnt(6)
	v_mfma_f32_32x32x16_bf16 v[64:79], v[80:83], v[108:111], v[64:79]
	ds_read_b128 v[156:159], v244 offset:18432
	ds_read_b128 v[160:163], v244 offset:20992
	s_waitcnt lgkmcnt(7)
	v_mfma_f32_32x32x16_bf16 v[64:79], v[84:87], v[112:115], v[64:79]
	ds_read_b128 v[164:167], v244 offset:23552
	ds_read_b128 v[152:155], v244 offset:26112
	s_waitcnt lgkmcnt(8)
	v_mfma_f32_32x32x16_bf16 v[64:79], v[88:91], v[116:119], v[64:79]
	ds_read_b128 v[148:151], v244 offset:18464
	ds_read_b128 v[144:147], v244 offset:21024
	ds_read_b128 v[136:139], v244 offset:23584
	ds_read_b128 v[140:143], v244 offset:26144
	s_waitcnt lgkmcnt(11)
	v_mfma_f32_32x32x16_bf16 v[80:95], v[220:223], v[104:107], 0
	s_waitcnt lgkmcnt(10)
	v_mfma_f32_32x32x16_bf16 v[80:95], v[224:227], v[108:111], v[80:95]
	v_exp_f32_e32 v64, v64
	v_exp_f32_e32 v65, v65
	v_exp_f32_e32 v66, v66
	v_exp_f32_e32 v67, v67
	v_exp_f32_e32 v68, v68
	v_exp_f32_e32 v69, v69
	s_waitcnt lgkmcnt(9)
	v_mfma_f32_32x32x16_bf16 v[80:95], v[236:239], v[112:115], v[80:95]
	v_exp_f32_e32 v70, v70
	v_exp_f32_e32 v71, v71
	v_exp_f32_e32 v72, v72
	v_exp_f32_e32 v73, v73
	v_exp_f32_e32 v74, v74
	v_exp_f32_e32 v75, v75
	s_waitcnt lgkmcnt(8)
	v_mfma_f32_32x32x16_bf16 v[80:95], v[240:243], v[116:119], v[80:95]
	v_exp_f32_e32 v76, v76
	v_exp_f32_e32 v77, v77
	v_exp_f32_e32 v78, v78
	v_exp_f32_e32 v79, v79
	v_cvt_pk_bf16_f32 v220, v64, v65
	v_cvt_pk_bf16_f32 v221, v66, v67
	v_cvt_pk_bf16_f32 v222, v68, v69
	v_cvt_pk_bf16_f32 v223, v70, v71
	v_cvt_pk_bf16_f32 v224, v72, v73
	v_cvt_pk_bf16_f32 v225, v74, v75
	v_cvt_pk_bf16_f32 v226, v76, v77
	v_cvt_pk_bf16_f32 v227, v78, v79
	s_waitcnt lgkmcnt(7)
	v_mfma_f32_32x32x16_bf16 v[48:63], v[220:223], v[156:159], v[48:63]
	ds_read_b128 v[156:159], v244 offset:28672
	v_exp_f32_e32 v80, v80
	v_exp_f32_e32 v81, v81
	v_exp_f32_e32 v82, v82
	s_waitcnt lgkmcnt(7)
	v_mfma_f32_32x32x16_bf16 v[32:47], v[220:223], v[160:163], v[32:47]
	ds_read_b128 v[160:163], v244 offset:31232
	v_exp_f32_e32 v83, v83
	v_exp_f32_e32 v84, v84
	v_exp_f32_e32 v85, v85
	s_waitcnt lgkmcnt(7)
	v_mfma_f32_32x32x16_bf16 v[16:31], v[220:223], v[164:167], v[16:31]
	ds_read_b128 v[164:167], v244 offset:33792
	v_exp_f32_e32 v86, v86
	v_exp_f32_e32 v87, v87
	v_exp_f32_e32 v88, v88
	s_waitcnt lgkmcnt(7)
	v_mfma_f32_32x32x16_bf16 v[0:15], v[220:223], v[152:155], v[0:15]
	ds_read_b128 v[152:155], v244 offset:36352
	v_exp_f32_e32 v89, v89
	v_exp_f32_e32 v90, v90
	v_exp_f32_e32 v91, v91
	s_waitcnt lgkmcnt(7)
	v_mfma_f32_32x32x16_bf16 v[48:63], v[224:227], v[148:151], v[48:63]
	ds_read_b128 v[148:151], v244 offset:28704
	v_exp_f32_e32 v92, v92
	v_exp_f32_e32 v93, v93
	v_exp_f32_e32 v94, v94
	v_exp_f32_e32 v95, v95
	s_waitcnt lgkmcnt(7)
	v_mfma_f32_32x32x16_bf16 v[32:47], v[224:227], v[144:147], v[32:47]
	ds_read_b128 v[144:147], v244 offset:31264
	v_cvt_pk_bf16_f32 v236, v80, v81
	v_cvt_pk_bf16_f32 v237, v82, v83
	v_cvt_pk_bf16_f32 v238, v84, v85
	v_add_f32_e32 v246, v66, v70
	v_add_f32_e32 v247, v67, v71
	v_add_f32_e32 v186, v186, v64
	v_add_f32_e32 v187, v187, v65
	s_waitcnt lgkmcnt(7)
	v_mfma_f32_32x32x16_bf16 v[16:31], v[224:227], v[136:139], v[16:31]
	ds_read_b128 v[136:139], v244 offset:33824
	v_cvt_pk_bf16_f32 v239, v86, v87
	v_cvt_pk_bf16_f32 v240, v88, v89
	v_cvt_pk_bf16_f32 v241, v90, v91
	v_add_f32_e32 v246, v246, v74
	v_add_f32_e32 v247, v247, v75
	v_add_f32_e32 v186, v186, v68
	v_add_f32_e32 v187, v187, v69
	s_waitcnt lgkmcnt(7)
	v_mfma_f32_32x32x16_bf16 v[0:15], v[224:227], v[140:143], v[0:15]
	ds_read_b128 v[140:143], v244 offset:36384
	v_cvt_pk_bf16_f32 v242, v92, v93
	v_cvt_pk_bf16_f32 v243, v94, v95
	v_add_f32_e32 v246, v246, v78
	v_add_f32_e32 v247, v247, v79
	v_add_f32_e32 v186, v186, v72
	v_add_f32_e32 v187, v187, v73
	s_andn2_b64 vcc, exec, s[8:9]
	s_cbranch_vccnz .Lat2_pvplain
; #define MFMA32(a, b, c) __builtin_amdgcn_mfma_f32_32x32x16_bf16((a), (b), (c), 0, 0, 0)
; DI unsigned pk_bf16(float lo, float hi) { f32x2 v = {lo, hi}; bf16v2 b = __builtin_convertvector(v, bf16v2); return __builtin_bit_cast(unsigned, b); }
; DI void attn_item(const Params& p, int g, int seq, int hd, int qt, int m, char* smem, int split_j, int sub) {
;     ...
;   auto load_tile = [&](int t, u32x4& k, u32x4& v0, u32x4& v1) __attribute__((always_inline)) {
;     k = *(const u32x4*)(ksrc + (size_t)(tbase + t) * 2048);
;     v0 = *(const u32x4*)(vsrc + (size_t)(tbase + t) * 4096); v1 = *(const u32x4*)(vsrc + (size_t)(tbase + t) * 4096 + 2048);
;   };
;   auto store_tile = [&](int buf, const u32x4& k, const u32x4& v0, const u32x4& v1) __attribute__((always_inline)) {
;     bf16_t* Kn = Ks + buf * 32 * 72; bf16_t* Vn = Vs + buf * 128 * 40;
;     *(u32x4*)(Kn + kr0 * 72 + kc) = k;
;     *(u32x4*)(Vn + vr0 * 40 + vc) = v0; *(u32x4*)(Vn + (vr0 + 64) * 40 + vc) = v1;
;   };
;     ...
;     bf16x8 pf[2];
; #pragma unroll
;     for (int s2 = 0; s2 < 2; ++s2) {
;       u32x4 w; w.x = pk_bf16(X[8 * s2], X[8 * s2 + 1]); w.y = pk_bf16(X[8 * s2 + 2], X[8 * s2 + 3]); w.z = pk_bf16(X[8 * s2 + 4], X[8 * s2 + 5]); w.w = pk_bf16(X[8 * s2 + 6], X[8 * s2 + 7]);
;       ls2 += (f32x2){X[8 * s2], X[8 * s2 + 1]}; ls2 += (f32x2){X[8 * s2 + 2], X[8 * s2 + 3]};
;       ls2 += (f32x2){X[8 * s2 + 4], X[8 * s2 + 5]}; ls2 += (f32x2){X[8 * s2 + 6], X[8 * s2 + 7]};
;       pf[s2] = __builtin_bit_cast(bf16x8, w);
;     }
; #pragma unroll
;     for (int s2 = 0; s2 < 2; ++s2)
; #pragma unroll
;       for (int dt = 0; dt < 4; ++dt) O[dt] = MFMA32(pf[s2], vf[s2][dt], O[dt]);
;   };
;   load_tile(0, rkA, rvA0, rvA1);
;   load_tile(1, rkB, rvB0, rvB1);
;   __syncthreads();
;   store_tile(0, rkA, rvA0, rvA1);
;   store_tile(1, rkB, rvB0, rvB1);
;   __syncthreads();
;   for (int it = 0; it < npairs; ++it) {
;     const int set = it & 1;
;     if (it + 1 < npairs) { load_tile(2 * it + 2, rkA, rvA0, rvA1); load_tile(2 * it + 3, rkB, rvB0, rvB1); }
;     compute(2 * it, 2 * set);
;     compute(2 * it + 1, 2 * set + 1);
;     if (it + 1 < npairs) { store_tile(2 * (set ^ 1), rkA, rvA0, rvA1); store_tile(2 * (set ^ 1) + 1, rkB, rvB0, rvB1); }
;     __syncthreads();
	s_add_i32 s10, s15, 1
	s_cmp_lt_u32 s10, s73
	s_cbranch_scc0 .Lat2_pvw
	s_xor_b32 s7, s16, 2
	s_mul_i32 s8, s7, 0x2800
	s_add_i32 s8, s8, 32
	s_mulk_i32 s7, 0x1200
	v_add_u32_e32 v192, s7, v169
	v_add3_u32 v244, s8, v189, v190
	s_addk_i32 s8, 0x2800
	s_add_i32 s13, s13, 64
	s_add_i32 s6, s6, 2
	s_mov_b32 s15, s10
	s_mov_b64 s[20:21], 0x1000
	s_waitcnt lgkmcnt(7)
	v_mfma_f32_32x32x16_bf16 v[48:63], v[236:239], v[156:159], v[48:63]
	s_waitcnt vmcnt(5)
	ds_write_b128 v192, v[96:99]
	s_waitcnt vmcnt(4)
	ds_write_b128 v244, v[100:103] offset:18432
	v_add_f32_e32 v186, v186, v76
	v_add_f32_e32 v187, v187, v77
	v_add_f32_e32 v186, v186, v246
	v_add_f32_e32 v187, v187, v247
	v_add_f32_e32 v246, v82, v86
	s_waitcnt lgkmcnt(8)
	v_mfma_f32_32x32x16_bf16 v[32:47], v[236:239], v[160:163], v[32:47]
	s_waitcnt vmcnt(3)
	ds_write_b128 v244, v[120:123] offset:23552
	s_waitcnt vmcnt(2)
	ds_write_b128 v192, v[124:127] offset:4608
	v_add_f32_e32 v247, v83, v87
	v_add_f32_e32 v186, v186, v80
	v_add_f32_e32 v187, v187, v81
	v_add_f32_e32 v246, v246, v90
	v_add_f32_e32 v247, v247, v91
	s_waitcnt lgkmcnt(9)
	v_mfma_f32_32x32x16_bf16 v[16:31], v[236:239], v[164:167], v[16:31]
	v_add3_u32 v192, s8, v189, v190
	s_waitcnt vmcnt(1)
	ds_write_b128 v192, v[128:131] offset:18432
	v_add_f32_e32 v186, v186, v84
	v_add_f32_e32 v187, v187, v85
	v_add_f32_e32 v246, v246, v94
	v_add_f32_e32 v247, v247, v95
	v_add_f32_e32 v186, v186, v88
	s_waitcnt lgkmcnt(9)
	v_mfma_f32_32x32x16_bf16 v[0:15], v[236:239], v[152:155], v[0:15]
	s_waitcnt vmcnt(0)
	ds_write_b128 v192, v[132:135] offset:23552
	v_add_f32_e32 v187, v187, v89
	v_add_f32_e32 v186, v186, v92
	v_add_f32_e32 v187, v187, v93
	v_add_f32_e32 v186, v186, v246
	v_add_f32_e32 v187, v187, v247
	s_add_i32 s10, s6, -3
	s_and_b32 s16, s10, 2
	s_mul_i32 s10, s16, 0x1200
	s_mul_i32 s18, s16, 0x2800
	v_add_u32_e32 v192, s10, v191
	v_add_u32_e32 v244, s18, v196
	s_waitcnt lgkmcnt(0)
	s_barrier
	v_mfma_f32_32x32x16_bf16 v[48:63], v[240:243], v[148:151], v[48:63]
	ds_read_b128 v[64:67], v192
	ds_read_b128 v[80:83], v192 offset:32
	ds_read_b128 v[84:87], v192 offset:64
	ds_read_b128 v[88:91], v192 offset:96
	s_add_i32 s50, s6, -1
	s_lshl_b64 s[10:11], s[50:51], 12
	v_lshl_add_u64 v[220:221], v[172:173], 0, s[10:11]
	v_mfma_f32_32x32x16_bf16 v[32:47], v[240:243], v[144:147], v[32:47]
	global_load_dwordx4 v[96:99], v[220:221], off
	s_lshl_b64 s[10:11], s[50:51], 13
	v_lshl_add_u64 v[222:223], v[170:171], 0, s[10:11]
	global_load_dwordx4 v[100:103], v[222:223], off
	v_lshl_add_u64 v[224:225], v[222:223], 0, s[20:21]
	v_mfma_f32_32x32x16_bf16 v[16:31], v[240:243], v[136:139], v[16:31]
	global_load_dwordx4 v[120:123], v[224:225], off
	s_mov_b32 s7, s51
	s_lshl_b64 s[10:11], s[6:7], 12
	v_lshl_add_u64 v[220:221], v[172:173], 0, s[10:11]
	global_load_dwordx4 v[124:127], v[220:221], off
	s_lshl_b64 s[10:11], s[6:7], 13
	v_lshl_add_u64 v[222:223], v[170:171], 0, s[10:11]
	v_mfma_f32_32x32x16_bf16 v[0:15], v[240:243], v[140:143], v[0:15]
	global_load_dwordx4 v[128:131], v[222:223], off
	v_lshl_add_u64 v[224:225], v[222:223], 0, s[20:21]
	global_load_dwordx4 v[132:135], v[224:225], off
	s_add_i32 s7, s14, s13
	s_cmpk_lt_i32 s7, 0xff42
	s_cselect_b32 s19, 1, 0
	s_cmpk_gt_i32 s7, 0x9e
	s_cselect_b32 s50, 1, 0
	s_cmp_eq_u32 s17, 2
	s_cselect_b32 s50, s50, 0
	s_or_b32 s19, s19, s50
	s_mov_b64 s[8:9], -1
	s_cmp_lg_u32 s19, 0
	s_cbranch_scc1 .Lat2_qka
	s_waitcnt lgkmcnt(0)
	s_branch .LBB0_319
